# early L1 invalidate + write-through stores in the four residual-output phases, whose barriers then skip the L2 write-back
# speedup vs baseline: 1.0018x; 1.0018x over previous
; DI unsigned xb_add(unsigned* q, unsigned v) { return __hip_atomic_fetch_add(q, v, __ATOMIC_RELAXED, __HIP_MEMORY_SCOPE_AGENT); }
; DI void grid_bar(unsigned* bar, volatile LAS unsigned* st, int wid) {
;     ...
;             if (old + 1u == (gen + 1u) * nloc) {
;                 __builtin_amdgcn_fence(__ATOMIC_RELEASE, "agent");
;                 asm volatile("s_waitcnt vmcnt(0)" ::: "memory");
;                 const unsigned og = xb_add(&bar[XB_TOP], 1u);
;                 const unsigned tg = og / nx;
;                 if (og + 1u == (tg + 1u) * nx) xb_add(&bar[XB_TOPGEN], 1u);
.LBB0_675:
	s_andn2_saveexec_b64 s[12:13], s[12:13]
	s_cbranch_execz .LBB0_695
	s_mov_b64 s[12:13], exec
	s_nop 0
	s_waitcnt lgkmcnt(0)
	s_waitcnt vmcnt(0)
	v_mbcnt_lo_u32_b32 v1, s12, 0
	v_mbcnt_hi_u32_b32 v1, s13, v1
	v_cmp_eq_u32_e32 vcc, 0, v1
	s_and_saveexec_b64 s[14:15], vcc
	s_cbranch_execz .LBB0_678
	s_bcnt1_i32_b64 s12, s[12:13]
	v_mov_b32_e32 v2, 0xcd83000
	v_mov_b32_e32 v3, s12
	global_atomic_add v2, v2, v3, s[8:9] offset:1024 sc0
